# v16 plus half-step-1 PV V-fragment tr-reads issued before the next-tile global loads
# baseline (speedup 1.0000x reference)
; __device__ __forceinline__ void finishSM(f32x16& p0, f32x16& p1, float alpha, float& l_reg, bf16x8& pa0, bf16x8& pa1, bf16x8& pa2, bf16x8& pa3) {
; #pragma unroll
;     for (int r = 0; r < 16; ++r) p1[r] = __builtin_amdgcn_exp2f(p1[r]);
;     float ps = 0;
; #pragma unroll
;     for (int r = 0; r < 16; ++r) ps += p0[r];
; #pragma unroll
;     for (int r = 0; r < 16; ++r) ps += p1[r];
;     { auto rr = __builtin_amdgcn_permlane32_swap(__float_as_uint(ps), __float_as_uint(ps), false, false);
;       ps = __uint_as_float(rr[0]) + __uint_as_float(rr[1]); }
;     l_reg = l_reg * alpha + ps;
;     PK4(p0, 0, pa0); PK4(p0, 8, pa1); PK4(p1, 0, pa2); PK4(p1, 8, pa3);
; }
; template <int KB>
; __device__ __forceinline__ void qkt(f32x16& p0, f32x16& p1, const char* K_lds, int r32, int hi, const bf16x8* qr, const char* qx) {
;     p0 = f32x16{}; p1 = f32x16{};
;     const char* kb[4];
; #pragma unroll
;     for (int dd = 0; dd < 4; ++dd) kb[dd] = K_lds + KB * SHM_K + KSWZ(r32, (dd * 16 + hi * 8) * 2);
; #pragma unroll
;     for (int d0 = 0; d0 < 12; ++d0) { const char* a = kb[d0 & 3] + (d0 >> 2) * 128;
;         bf16x8 b0 = *reinterpret_cast<const bf16x8*>(a);
;         bf16x8 b1 = *reinterpret_cast<const bf16x8*>(a + 32 * 384);
;         const bf16x8 q = d0 < 8 ? qr[d0 & 7] : *reinterpret_cast<const bf16x8*>(qx + (d0 - 8) * 1024);
;         p0 = __builtin_amdgcn_mfma_f32_32x32x16_bf16(b0, q, p0, 0, 0, 0);
;         p1 = __builtin_amdgcn_mfma_f32_32x32x16_bf16(b1, q, p1, 0, 0, 0); }
.LBB0_971:
	ds_read_b128 v[178:181], v194 offset:24576
	ds_read_b128 v[220:223], v194 offset:36864
	ds_read_b128 v[224:227], v195 offset:24576
	ds_read_b128 v[228:231], v195 offset:36864
	ds_read_b128 v[232:235], v196 offset:24576
	ds_read_b128 v[236:239], v196 offset:36864
	v_add_f32_e32 v149, 0, v159
	v_add_f32_e32 v149, v161, v149
	s_nop 1
	v_add_f32_e32 v149, v157, v149
	v_add_f32_e32 v149, v160, v149
	s_waitcnt lgkmcnt(5)
	v_mfma_f32_32x32x16_bf16 v[80:95], v[178:181], v[124:127], 0
	v_add_f32_e32 v149, v156, v149
	v_add_f32_e32 v149, v158, v149
	v_add_f32_e32 v149, v154, v149
	s_waitcnt lgkmcnt(4)
	v_mfma_f32_32x32x16_bf16 v[64:79], v[220:223], v[124:127], 0
	ds_read_b128 v[178:181], v197 offset:24576
	ds_read_b128 v[220:223], v197 offset:36864
	v_add_f32_e32 v149, v155, v149
	v_add_f32_e32 v149, v150, v149
	s_nop 1
	v_add_f32_e32 v149, v153, v149
	s_waitcnt lgkmcnt(5)
	v_mfma_f32_32x32x16_bf16 v[80:95], v[224:227], v[120:123], v[80:95]
	v_add_f32_e32 v149, v146, v149
	v_add_f32_e32 v149, v151, v149
	v_exp_f32_e32 v142, v142
	s_waitcnt lgkmcnt(4)
	v_mfma_f32_32x32x16_bf16 v[64:79], v[228:231], v[120:123], v[64:79]
	ds_read_b128 v[224:227], v194 offset:24704
	ds_read_b128 v[228:231], v194 offset:36992
	v_add_f32_e32 v149, v144, v149
	v_exp_f32_e32 v143, v143
	v_add_f32_e32 v149, v152, v149
	s_waitcnt lgkmcnt(5)
	v_mfma_f32_32x32x16_bf16 v[80:95], v[232:235], v[116:119], v[80:95]
	v_exp_f32_e32 v140, v140
	v_add_f32_e32 v149, v145, v149
	v_exp_f32_e32 v141, v141
	s_waitcnt lgkmcnt(4)
	v_mfma_f32_32x32x16_bf16 v[64:79], v[236:239], v[116:119], v[64:79]
	ds_read_b128 v[232:235], v195 offset:24704
	ds_read_b128 v[236:239], v195 offset:36992
	v_add_f32_e32 v149, v147, v149
	v_exp_f32_e32 v138, v138
	v_add_f32_e32 v149, v142, v149
	s_waitcnt lgkmcnt(5)
	v_mfma_f32_32x32x16_bf16 v[80:95], v[178:181], v[112:115], v[80:95]
	v_exp_f32_e32 v139, v139
	s_nop 1
	v_add_f32_e32 v149, v143, v149
	v_exp_f32_e32 v136, v136
	s_waitcnt lgkmcnt(4)
	v_mfma_f32_32x32x16_bf16 v[64:79], v[220:223], v[112:115], v[64:79]
	ds_read_b128 v[178:181], v196 offset:24704
	ds_read_b128 v[220:223], v196 offset:36992
	v_add_f32_e32 v149, v140, v149
	v_exp_f32_e32 v137, v137
	v_add_f32_e32 v149, v141, v149
	s_waitcnt lgkmcnt(5)
	v_mfma_f32_32x32x16_bf16 v[80:95], v[224:227], v[108:111], v[80:95]
	v_exp_f32_e32 v134, v134
	s_nop 1
	v_add_f32_e32 v149, v138, v149
	v_exp_f32_e32 v135, v135
	s_waitcnt lgkmcnt(4)
	v_mfma_f32_32x32x16_bf16 v[64:79], v[228:231], v[108:111], v[64:79]
	ds_read_b128 v[224:227], v197 offset:24704
	ds_read_b128 v[228:231], v197 offset:36992
	v_add_f32_e32 v149, v139, v149
	v_exp_f32_e32 v132, v132
	v_add_f32_e32 v149, v136, v149
	s_waitcnt lgkmcnt(5)
	v_mfma_f32_32x32x16_bf16 v[80:95], v[232:235], v[104:107], v[80:95]
	v_exp_f32_e32 v133, v133
	v_add_f32_e32 v149, v137, v149
	s_nop 1
	v_exp_f32_e32 v130, v130
	s_waitcnt lgkmcnt(4)
	v_mfma_f32_32x32x16_bf16 v[64:79], v[236:239], v[104:107], v[64:79]
	ds_read_b128 v[240:243], v204
	ds_read_b128 v[232:235], v194 offset:24832
	ds_read_b128 v[236:239], v194 offset:37120
	v_add_f32_e32 v149, v134, v149
	v_exp_f32_e32 v131, v131
	v_add_f32_e32 v149, v135, v149
	s_waitcnt lgkmcnt(6)
	v_mfma_f32_32x32x16_bf16 v[80:95], v[178:181], v[100:103], v[80:95]
	v_exp_f32_e32 v128, v128
	v_add_f32_e32 v149, v132, v149
	s_nop 1
	v_exp_f32_e32 v129, v129
	s_waitcnt lgkmcnt(5)
	v_mfma_f32_32x32x16_bf16 v[64:79], v[220:223], v[100:103], v[64:79]
	ds_read_b128 v[244:247], v204 offset:1024
	ds_read_b128 v[178:181], v195 offset:24832
	ds_read_b128 v[220:223], v195 offset:37120
	v_add_f32_e32 v149, v133, v149
	v_add_f32_e32 v149, v130, v149
	v_add_f32_e32 v149, v131, v149
	s_waitcnt lgkmcnt(7)
	v_mfma_f32_32x32x16_bf16 v[80:95], v[224:227], v[96:99], v[80:95]
	v_add_f32_e32 v149, v128, v149
	v_add_f32_e32 v211, v129, v149
	s_nop 1
	v_mov_b32_e32 v212, v211
	s_waitcnt lgkmcnt(6)
	v_mfma_f32_32x32x16_bf16 v[64:79], v[228:231], v[96:99], v[64:79]
	ds_read_b128 v[224:227], v196 offset:24832
	ds_read_b128 v[228:231], v196 offset:37120
	s_nop 1
	v_permlane32_swap_b32_e32 v211, v212
	v_cvt_pk_bf16_f32 v214, v159, v161
	s_waitcnt lgkmcnt(6)
	v_mfma_f32_32x32x16_bf16 v[80:95], v[232:235], v[240:243], v[80:95]
	v_cvt_pk_bf16_f32 v215, v157, v160
	v_cvt_pk_bf16_f32 v216, v156, v158
	v_cvt_pk_bf16_f32 v217, v154, v155
	s_waitcnt lgkmcnt(5)
	v_mfma_f32_32x32x16_bf16 v[64:79], v[236:239], v[240:243], v[64:79]
	ds_read_b128 v[232:235], v197 offset:24832
	ds_read_b128 v[236:239], v197 offset:37120
	ds_read_b128 v[240:243], v204 offset:2048
	v_cvt_pk_bf16_f32 v150, v150, v153
	v_cvt_pk_bf16_f32 v151, v146, v151
	v_cvt_pk_bf16_f32 v152, v144, v152
	s_waitcnt lgkmcnt(6)
	v_mfma_f32_32x32x16_bf16 v[80:95], v[178:181], v[244:247], v[80:95]
	v_cvt_pk_bf16_f32 v153, v145, v147
	v_cvt_pk_bf16_f32 v154, v142, v143
	v_cvt_pk_bf16_f32 v155, v140, v141
	s_waitcnt lgkmcnt(5)
	v_mfma_f32_32x32x16_bf16 v[64:79], v[220:223], v[244:247], v[64:79]
	ds_read_b128 v[244:247], v204 offset:3072
	v_cvt_pk_bf16_f32 v156, v138, v139
	v_cvt_pk_bf16_f32 v157, v136, v137
	v_cvt_pk_bf16_f32 v158, v134, v135
	s_waitcnt lgkmcnt(1)
	v_mfma_f32_32x32x16_bf16 v[80:95], v[224:227], v[240:243], v[80:95]
	v_cvt_pk_bf16_f32 v159, v132, v133
	v_cvt_pk_bf16_f32 v160, v130, v131
	v_cvt_pk_bf16_f32 v161, v128, v129
	s_waitcnt lgkmcnt(4)
	v_mfma_f32_32x32x16_bf16 v[64:79], v[228:231], v[240:243], v[64:79]
	s_nop 0
	v_permlane32_swap_b32_e32 v214, v216
	v_permlane32_swap_b32_e32 v215, v217
	s_waitcnt lgkmcnt(0)
	v_mfma_f32_32x32x16_bf16 v[80:95], v[232:235], v[244:247], v[80:95]
	v_permlane32_swap_b32_e32 v150, v152
	v_permlane32_swap_b32_e32 v151, v153
	v_permlane32_swap_b32_e32 v154, v156
	s_waitcnt lgkmcnt(2)
; template <int VB>
; __device__ __forceinline__ void pv_tile(f32x16* o, int vb0, bf16x8 pa0, bf16x8 pa1, bf16x8 pa2, bf16x8 pa3) {
;     ...
;     PV_D2(0, 1); PV_D2(2, 3);
	v_mfma_f32_32x32x16_bf16 v[64:79], v[236:239], v[244:247], v[64:79]
	v_permlane32_swap_b32_e32 v155, v157
	v_permlane32_swap_b32_e32 v158, v160
	v_permlane32_swap_b32_e32 v159, v161
	ds_read_b64_tr_b16 v[218:219], v188 offset:0
	ds_read_b64_tr_b16 v[220:221], v188 offset:0x800
	ds_read_b64_tr_b16 v[222:223], v188 offset:0x200
	ds_read_b64_tr_b16 v[224:225], v188 offset:0xa00
	ds_read_b64_tr_b16 v[226:227], v188 offset:0x1000
	ds_read_b64_tr_b16 v[228:229], v188 offset:0x1800
	ds_read_b64_tr_b16 v[230:231], v188 offset:0x1200
	ds_read_b64_tr_b16 v[232:233], v188 offset:0x1a00
	ds_read_b64_tr_b16 v[234:235], v188 offset:0x2000
	ds_read_b64_tr_b16 v[236:237], v188 offset:0x2800
	ds_read_b64_tr_b16 v[238:239], v188 offset:0x2200
	ds_read_b64_tr_b16 v[240:241], v188 offset:0x2a00
	ds_read_b64_tr_b16 v[242:243], v188 offset:0x3000
	ds_read_b64_tr_b16 v[244:245], v188 offset:0x3800
	ds_read_b64_tr_b16 v[246:247], v188 offset:0x3200
	ds_read_b64_tr_b16 v[248:249], v188 offset:0x3a00
	v_lshl_add_u64 v[180:181], s[70:71], 0, v[170:171]
	v_add_co_u32_e32 v128, vcc, s76, v180
	v_lshl_add_u64 v[178:179], s[96:97], 0, v[170:171]
	s_nop 0
	v_addc_co_u32_e32 v129, vcc, 0, v181, vcc
	v_add_co_u32_e32 v132, vcc, s77, v180
	s_nop 1
	v_addc_co_u32_e32 v133, vcc, 0, v181, vcc
	v_add_co_u32_e32 v136, vcc, s76, v178
	s_nop 1
	v_addc_co_u32_e32 v137, vcc, 0, v179, vcc
	v_add_co_u32_e32 v140, vcc, s77, v178
	s_nop 1
	v_addc_co_u32_e32 v141, vcc, 0, v179, vcc
	global_load_dwordx4 v[136:139], v[136:137], off
	global_load_dwordx4 v[140:143], v[140:141], off
	global_load_dwordx4 v[144:147], v[176:177], off
	global_load_dwordx4 v[128:131], v[128:129], off
	global_load_dwordx4 v[132:135], v[132:133], off
	s_waitcnt lgkmcnt(14)
	s_nop 0
	v_mfma_f32_32x32x16_bf16 v[48:63], v[214:217], v[218:221], v[48:63]
	ds_read_b64_tr_b16 v[218:219], v188 offset:0x400
	ds_read_b64_tr_b16 v[220:221], v188 offset:0xc00
	s_waitcnt lgkmcnt(14)
	v_mfma_f32_32x32x16_bf16 v[32:47], v[214:217], v[222:225], v[32:47]
	ds_read_b64_tr_b16 v[222:223], v188 offset:0x600
	ds_read_b64_tr_b16 v[224:225], v188 offset:0xe00
	s_waitcnt lgkmcnt(14)
	v_mfma_f32_32x32x16_bf16 v[48:63], v[150:153], v[226:229], v[48:63]
	ds_read_b64_tr_b16 v[226:227], v188 offset:0x1400
	ds_read_b64_tr_b16 v[228:229], v188 offset:0x1c00
	s_waitcnt lgkmcnt(14)
	v_mfma_f32_32x32x16_bf16 v[32:47], v[150:153], v[230:233], v[32:47]
	ds_read_b64_tr_b16 v[230:231], v188 offset:0x1600
	ds_read_b64_tr_b16 v[232:233], v188 offset:0x1e00
	s_waitcnt lgkmcnt(14)
	v_mfma_f32_32x32x16_bf16 v[48:63], v[154:157], v[234:237], v[48:63]
	ds_read_b64_tr_b16 v[234:235], v188 offset:0x2400
	ds_read_b64_tr_b16 v[236:237], v188 offset:0x2c00
	s_waitcnt lgkmcnt(14)
	v_mfma_f32_32x32x16_bf16 v[32:47], v[154:157], v[238:241], v[32:47]
	ds_read_b64_tr_b16 v[238:239], v188 offset:0x2600
	ds_read_b64_tr_b16 v[240:241], v188 offset:0x2e00
	s_waitcnt lgkmcnt(14)
	v_mfma_f32_32x32x16_bf16 v[48:63], v[158:161], v[242:245], v[48:63]
	ds_read_b64_tr_b16 v[242:243], v188 offset:0x3400
	ds_read_b64_tr_b16 v[244:245], v188 offset:0x3c00
	s_waitcnt lgkmcnt(14)
	v_mfma_f32_32x32x16_bf16 v[32:47], v[158:161], v[246:249], v[32:47]
	ds_read_b64_tr_b16 v[250:251], v188 offset:0x3600
	ds_read_b64_tr_b16 v[252:253], v188 offset:0x3e00
	s_waitcnt lgkmcnt(14)
	v_mfma_f32_32x32x16_bf16 v[16:31], v[214:217], v[218:221], v[16:31]
	s_sub_i32 s0, s68, 64
	s_cmp_le_i32 s0, s95
	s_waitcnt lgkmcnt(12)
	v_mfma_f32_32x32x16_bf16 v[0:15], v[214:217], v[222:225], v[0:15]
	s_waitcnt lgkmcnt(10)
	v_mfma_f32_32x32x16_bf16 v[16:31], v[150:153], v[226:229], v[16:31]
	s_waitcnt lgkmcnt(8)
	v_mfma_f32_32x32x16_bf16 v[0:15], v[150:153], v[230:233], v[0:15]
	s_waitcnt lgkmcnt(6)
	v_mfma_f32_32x32x16_bf16 v[16:31], v[154:157], v[234:237], v[16:31]
	s_waitcnt lgkmcnt(4)
	v_mfma_f32_32x32x16_bf16 v[0:15], v[154:157], v[238:241], v[0:15]
	s_waitcnt lgkmcnt(2)
	v_mfma_f32_32x32x16_bf16 v[16:31], v[158:161], v[242:245], v[16:31]
	s_waitcnt lgkmcnt(0)
	v_mfma_f32_32x32x16_bf16 v[0:15], v[158:161], v[250:253], v[0:15]
	s_waitcnt vmcnt(2)
	ds_write_b128 v169, v[136:139]
	ds_write_b128 v169, v[140:143] offset:12288
	ds_write_b128 v182, v[144:147]
	s_cbranch_scc1 .LBB0_973
; __device__ __forceinline__ void mask_tile(f32x16& p0, f32x16& p1, int dq) {
;     const float NEG = -__builtin_inff();
; #pragma unroll
;     for (int r = 0; r < 16; ++r) { const int c = (r & 3) + 8 * (r >> 2); if (dq - c < 0) p0[r] = NEG; if (dq - c - 32 < 0) p1[r] = NEG; }
; }
	v_add_u32_e32 v149, 64, v210
	v_cmp_gt_i32_e64 s[64:65], 26, v149
	v_cmp_gt_i32_e64 s[66:67], 27, v149
	v_cmp_gt_i32_e64 s[62:63], 25, v149
	s_and_b64 s[64:65], s[66:67], s[64:65]
	v_cmp_gt_i32_e64 s[60:61], 24, v149
	s_and_b64 s[62:63], s[64:65], s[62:63]
	v_cmp_gt_i32_e64 s[58:59], 19, v149
	s_and_b64 s[60:61], s[62:63], s[60:61]
	v_cmp_gt_i32_e64 s[56:57], 18, v149
	s_and_b64 s[58:59], s[60:61], s[58:59]
	v_cmp_gt_i32_e64 s[54:55], 17, v149
	s_and_b64 s[56:57], s[58:59], s[56:57]
	v_cmp_gt_i32_e64 s[52:53], 16, v149
	s_and_b64 s[54:55], s[56:57], s[54:55]
	v_cmp_gt_i32_e64 s[50:51], 11, v149
	s_and_b64 s[52:53], s[54:55], s[52:53]
	v_cmp_gt_i32_e64 s[48:49], 10, v149
	s_and_b64 s[50:51], s[52:53], s[50:51]
	v_cmp_gt_i32_e64 s[46:47], 9, v149
	s_and_b64 s[48:49], s[50:51], s[48:49]
	v_cmp_gt_i32_e64 s[44:45], 8, v149
	s_and_b64 s[46:47], s[48:49], s[46:47]
	v_cmp_gt_i32_e64 s[42:43], 3, v149
	s_and_b64 s[44:45], s[46:47], s[44:45]
	v_cmp_gt_i32_e64 s[40:41], 2, v149
	s_and_b64 s[42:43], s[44:45], s[42:43]
	v_cmp_gt_i32_e64 s[38:39], 1, v149
	s_and_b64 s[40:41], s[42:43], s[40:41]
	v_cmp_gt_i32_e64 s[34:35], 0, v149
	s_and_b64 s[38:39], s[40:41], s[38:39]
	s_and_b64 s[34:35], s[38:39], s[34:35]
	v_cmp_gt_i32_e64 s[30:31], 58, v149
	v_cndmask_b32_e64 v80, v80, v198, s[34:35]
	v_cmp_gt_i32_e64 s[34:35], 59, v149
	v_cmp_gt_i32_e64 s[28:29], 57, v149
	s_and_b64 s[30:31], s[34:35], s[30:31]
	v_cmp_gt_i32_e64 s[26:27], 56, v149
	s_and_b64 s[28:29], s[30:31], s[28:29]
	v_cmp_gt_i32_e64 s[24:25], 51, v149
	s_and_b64 s[26:27], s[28:29], s[26:27]
	v_cmp_gt_i32_e64 s[22:23], 50, v149
	s_and_b64 s[24:25], s[26:27], s[24:25]
	v_cmp_gt_i32_e64 s[20:21], 49, v149
	s_and_b64 s[22:23], s[24:25], s[22:23]
	v_cmp_gt_i32_e64 s[18:19], 48, v149
	s_and_b64 s[20:21], s[22:23], s[20:21]
	v_cmp_gt_i32_e64 s[16:17], 43, v149
	s_and_b64 s[18:19], s[20:21], s[18:19]
	v_cmp_gt_i32_e64 s[14:15], 42, v149
	s_and_b64 s[16:17], s[18:19], s[16:17]
	v_cmp_gt_i32_e64 s[12:13], 41, v149
	s_and_b64 s[14:15], s[16:17], s[14:15]
	v_cmp_gt_i32_e64 s[10:11], 40, v149
	s_and_b64 s[12:13], s[14:15], s[12:13]
	v_cmp_gt_i32_e64 s[8:9], 35, v149
	s_and_b64 s[10:11], s[12:13], s[10:11]
	v_cmp_gt_i32_e64 s[6:7], 34, v149
	s_and_b64 s[8:9], s[10:11], s[8:9]
	v_cmp_gt_i32_e64 s[0:1], 33, v149
	s_and_b64 s[6:7], s[8:9], s[6:7]
	v_cmp_gt_i32_e32 vcc, 32, v149
	s_and_b64 s[0:1], s[6:7], s[0:1]
	s_and_b64 vcc, s[0:1], vcc
	v_cndmask_b32_e64 v95, v95, v198, s[66:67]
	v_cndmask_b32_e64 v94, v94, v198, s[64:65]
	v_cndmask_b32_e64 v93, v93, v198, s[62:63]
	v_cndmask_b32_e64 v92, v92, v198, s[60:61]
	v_cndmask_b32_e64 v91, v91, v198, s[58:59]
	v_cndmask_b32_e64 v90, v90, v198, s[56:57]
	v_cndmask_b32_e64 v89, v89, v198, s[54:55]
	v_cndmask_b32_e64 v88, v88, v198, s[52:53]
	v_cndmask_b32_e64 v87, v87, v198, s[50:51]
	v_cndmask_b32_e64 v86, v86, v198, s[48:49]
	v_cndmask_b32_e64 v85, v85, v198, s[46:47]
	v_cndmask_b32_e64 v84, v84, v198, s[44:45]
	v_cndmask_b32_e64 v83, v83, v198, s[42:43]
	v_cndmask_b32_e64 v82, v82, v198, s[40:41]
	v_cndmask_b32_e64 v81, v81, v198, s[38:39]
	v_cndmask_b32_e64 v79, v79, v198, s[34:35]
	v_cndmask_b32_e64 v78, v78, v198, s[30:31]
	v_cndmask_b32_e64 v77, v77, v198, s[28:29]
	v_cndmask_b32_e64 v76, v76, v198, s[26:27]
	v_cndmask_b32_e64 v75, v75, v198, s[24:25]
	v_cndmask_b32_e64 v74, v74, v198, s[22:23]
	v_cndmask_b32_e64 v73, v73, v198, s[20:21]
	v_cndmask_b32_e64 v72, v72, v198, s[18:19]
	v_cndmask_b32_e64 v71, v71, v198, s[16:17]
	v_cndmask_b32_e64 v70, v70, v198, s[14:15]
	v_cndmask_b32_e64 v69, v69, v198, s[12:13]
	v_cndmask_b32_e64 v68, v68, v198, s[10:11]
	v_cndmask_b32_e64 v67, v67, v198, s[8:9]
	v_cndmask_b32_e64 v66, v66, v198, s[6:7]
	v_cndmask_b32_e64 v65, v65, v198, s[0:1]
	v_cndmask_b32_e32 v64, v64, v198, vcc
